# MLA tile loops: V^T tile with 144-B rows and packed-P key order, fragments via one ds_read_b128 (slot 0x5800)
# baseline (speedup 1.0000x reference)
; #define LAS __attribute__((address_space(3)))
; #define MLA_GLOAD(t) do { const size_t ko = (size_t)(64 * (t)); rk = *(const u32x4*)(gk + ko * 64); if (lo256) rr = *(const u32x4*)(gr + ko * 32); rv = *(const u32x4*)(gv + ko); } while (0)
; #define MLA_LSTORE(buf) do { LAS unsigned char* kb_ = lds + (buf) * TILE; *(LAS u32x4*)(kb_ + (tid >> 3) * KS + (tid & 7) * 16) = rk; \
;         if (lo256) *(LAS u32x4*)(kb_ + (tid >> 2) * KS + 128 + (tid & 3) * 16) = rr; lds_store16_as2x8(kb_ + VOFF + (tid >> 3) * VS + (tid & 7) * 16, rv); } while (0)
; DI void pv_sub2(const LAS unsigned char* vt, int vstride, int koff_bytes, const f32x16& p0, const f32x16& p1, f32x16 (&o0)[2], f32x16 (&o1)[2], int r, int hh) {
;     ...
;             const LAS unsigned char* a = vt + (32 * u + r) * vstride + koff_bytes + 32 * st + 8 * hh;
;             lo[u] = *(const LAS u32x2*)a; hi[u] = *(const LAS u32x2*)(a + 16);
; DI void mla_qblock(int wv, int w, LAS unsigned char* lds, const bf16_t* Q, const bf16_t* KN, const bf16_t* KR, const bf16_t* VT, bf16_t* O, size_t tok0, int h, int qb) {
;     ...
;     u32x4 rk, rr, rv;
;     const bf16_t* gk = KN + ((tok0 >> 11) * 16 + h) * (size_t)(2048 * 64) + (size_t)tid * 8;
;     const bf16_t* gr = KR + tok0 * 32 + (size_t)tid * 8;
;     const bf16_t* gv = VT + ((tok0 >> 11) * 1024 + h * 64 + (tid >> 3)) * (size_t)VPITCH + (tid & 7) * 8;
;     ...
;     MLA_GLOAD(0); MLA_LSTORE(0); if (nt > 1) MLA_GLOAD(1); __syncthreads();
.LBB0_2818:
	s_or_b64 exec, exec, s[2:3]
	v_mul_u32_u24_e32 v2, 0x90, v12
	v_and_b32_e32 v3, 0x60, v11
	v_add_u32_e32 v2, v2, v3
	v_and_b32_e32 v3, 1, v10
	v_lshl_add_u32 v2, v3, 3, v2
	v_add_u32_e32 v0, s81, v2
	v_add_co_u32_e32 v2, vcc, 0x2000, v186
	s_waitcnt lgkmcnt(0)
	ds_write2_b64 v0, v[6:7], v[8:9] offset1:2
	v_addc_co_u32_e32 v3, vcc, 0, v187, vcc
	global_load_dwordx4 v[164:167], v[2:3], off
	s_and_saveexec_b64 s[2:3], s[0:1]
	s_cbranch_execz .LBB0_2820
	v_add_co_u32_e32 v2, vcc, 0x1000, v188
	s_nop 1
	v_addc_co_u32_e32 v3, vcc, 0, v189, vcc
	flat_load_dwordx4 v[160:163], v[2:3]
.LBB0_2820:
	s_or_b64 exec, exec, s[2:3]
	flat_load_dwordx4 v[168:171], v[192:193] offset:128
	s_lshl_b32 s46, s4, 3
	v_lshlrev_b32_e32 v191, 4, v202
	v_mul_u32_u24_e32 v195, 0x90, v12
	v_and_b32_e32 v2, 0x60, v11
	v_add_u32_e32 v195, v195, v2
	v_and_b32_e32 v2, 1, v10
	v_lshl_add_u32 v195, v2, 3, v195
	s_cmp_lg_u32 s4, 0
	v_cmp_eq_u32_e64 s[2:3], 0, v202
	v_mul_u32_u24_e32 v203, 0x90, v194
	v_mul_u32_u24_e32 v204, 0x90, v194
	v_add_u32_e32 v204, 0x1200, v204
	s_waitcnt lgkmcnt(0)
	s_barrier
	s_cbranch_scc0 .LBB0_2878
	v_cmp_lt_i32_e32 vcc, v223, v222
	v_mov_b32_e32 v14, v1
	v_mov_b32_e32 v15, v1
	v_cndmask_b32_e32 v0, v207, v223, vcc
	v_lshlrev_b32_e32 v205, 2, v0
	v_mov_b32_e32 v0, v1
	v_mov_b32_e32 v2, v1
	v_mov_b32_e32 v3, v1
	v_mov_b32_e32 v4, v1
	v_mov_b32_e32 v5, v1
	v_mov_b32_e32 v6, v1
	v_mov_b32_e32 v7, v1
	v_mov_b32_e32 v8, v1
	v_mov_b32_e32 v9, v1
	v_mov_b32_e32 v10, v1
	v_mov_b32_e32 v11, v1
	v_mov_b32_e32 v12, v1
	v_mov_b32_e32 v13, v1
	v_mov_b32_e32 v196, 0
	s_waitcnt vmcnt(0)
	v_mov_b64_e32 v[152:153], v[164:165]
	v_mov_b64_e32 v[148:149], v[160:161]
	v_mov_b64_e32 v[156:157], v[168:169]
	v_mov_b64_e32 v[66:67], v[14:15]
	v_mov_b64_e32 v[50:51], v[14:15]
	s_mov_b32 s22, 0
	v_cndmask_b32_e64 v172, 0, v232, s[2:3]
	v_cndmask_b32_e64 v173, 0, v228, s[2:3]
	v_mov_b32_e32 v174, v1
	v_mov_b32_e32 v175, v1
	v_mul_u32_u24_e32 v197, 0x90, v194
	v_mul_u32_u24_e32 v198, 0x90, v194
	v_add_u32_e32 v198, 0x1200, v198
	v_mov_b64_e32 v[154:155], v[166:167]
	v_mov_b64_e32 v[150:151], v[162:163]
	v_mov_b64_e32 v[158:159], v[170:171]
	s_mov_b32 s47, 0
	v_mov_b64_e32 v[64:65], v[12:13]
	v_mov_b64_e32 v[62:63], v[10:11]
	v_mov_b64_e32 v[60:61], v[8:9]
	v_mov_b64_e32 v[58:59], v[6:7]
	v_mov_b64_e32 v[56:57], v[4:5]
	v_mov_b64_e32 v[54:55], v[2:3]
	v_mov_b64_e32 v[52:53], v[0:1]
	v_mov_b64_e32 v[48:49], v[12:13]
	v_mov_b64_e32 v[46:47], v[10:11]
	v_mov_b64_e32 v[44:45], v[8:9]
	v_mov_b64_e32 v[42:43], v[6:7]
	v_mov_b64_e32 v[40:41], v[4:5]
	v_mov_b64_e32 v[38:39], v[2:3]
	v_mov_b64_e32 v[36:37], v[0:1]
	v_mov_b32_e32 v201, 0
	v_mov_b32_e32 v200, 0
	v_mov_b32_e32 v199, 0
	v_mov_b32_e32 v4, 0
	v_mov_b32_e32 v5, v196
	v_mov_b32_e32 v6, v196
	v_mov_b32_e32 v7, v196
	v_mov_b32_e32 v8, v196
	v_mov_b32_e32 v9, v196
	v_mov_b32_e32 v10, v196
	v_mov_b32_e32 v11, v196
	v_mov_b32_e32 v12, v196
	v_mov_b32_e32 v13, v196
	v_mov_b32_e32 v14, v196
	v_mov_b32_e32 v15, v196
	v_mov_b32_e32 v16, v196
	v_mov_b32_e32 v17, v196
	v_mov_b32_e32 v18, v196
	v_mov_b32_e32 v19, v196
	v_mov_b32_e32 v20, v196
	v_mov_b32_e32 v21, v196
	v_mov_b32_e32 v22, v196
	v_mov_b32_e32 v23, v196
	v_mov_b32_e32 v24, v196
	v_mov_b32_e32 v25, v196
	v_mov_b32_e32 v26, v196
	v_mov_b32_e32 v27, v196
	v_mov_b32_e32 v28, v196
	v_mov_b32_e32 v29, v196
	v_mov_b32_e32 v30, v196
	v_mov_b32_e32 v31, v196
	v_mov_b32_e32 v32, v196
	v_mov_b32_e32 v33, v196
	v_mov_b32_e32 v34, v196
	v_mov_b32_e32 v35, v196
; #define LAS __attribute__((address_space(3)))
; DI f32x16 mfma32(bf16x8 a, bf16x8 b, f32x16 c) { return __builtin_amdgcn_mfma_f32_32x32x16_bf16(a, b, c, 0, 0, 0); }
; #define MLA_GLOAD(t) do { const size_t ko = (size_t)(64 * (t)); rk = *(const u32x4*)(gk + ko * 64); if (lo256) rr = *(const u32x4*)(gr + ko * 32); rv = *(const u32x4*)(gv + ko); } while (0)
; #define MLA_LSTORE(buf) do { LAS unsigned char* kb_ = lds + (buf) * TILE; *(LAS u32x4*)(kb_ + (tid >> 3) * KS + (tid & 7) * 16) = rk; \
;         if (lo256) *(LAS u32x4*)(kb_ + (tid >> 2) * KS + 128 + (tid & 3) * 16) = rr; lds_store16_as2x8(kb_ + VOFF + (tid >> 3) * VS + (tid & 7) * 16, rv); } while (0)
; DI void pv_sub2(const LAS unsigned char* vt, int vstride, int koff_bytes, const f32x16& p0, const f32x16& p1, f32x16 (&o0)[2], f32x16 (&o1)[2], int r, int hh) {
; #pragma unroll
;     for (int st = 0; st < 2; ++st) {
;         u32x2 lo[2], hi[2];
; #pragma unroll
;         for (int u = 0; u < 2; ++u) {
;             const LAS unsigned char* a = vt + (32 * u + r) * vstride + koff_bytes + 32 * st + 8 * hh;
;             lo[u] = *(const LAS u32x2*)a; hi[u] = *(const LAS u32x2*)(a + 16);
;         }
;         const bf16x8 pf0 = st ? pack8<1>(p0) : pack8<0>(p0), pf1 = st ? pack8<1>(p1) : pack8<0>(p1);
;         __builtin_amdgcn_sched_barrier(0);
; #pragma unroll
;         for (int u = 0; u < 2; ++u) { u32x4 v; v.x = lo[u].x; v.y = lo[u].y; v.z = hi[u].x; v.w = hi[u].y; const bf16x8 vf = __builtin_bit_cast(bf16x8, v);
;             o0[u] = mfma32(vf, pf0, o0[u]); o1[u] = mfma32(vf, pf1, o1[u]); }
;     }
; DI void mla_qblock(int wv, int w, LAS unsigned char* lds, const bf16_t* Q, const bf16_t* KN, const bf16_t* KR, const bf16_t* VT, bf16_t* O, size_t tok0, int h, int qb) {
;     ...
;     for (int t = 0; t < nfull; ++t) {
;         const int bn = bi == 2 ? 0 : bi + 1;
;         MLA_LSTORE(bn);
;         if (t + 2 < nt) MLA_GLOAD(t + 2);
;         const LAS unsigned char* kb = lds + bi * TILE;
; #pragma nounroll
;         for (int tt = 0; tt < 2; ++tt) {
;             f32x16 s0, s1;
;             MLA_QK1(tt);
;             softmax_lazy1(s0, m0, l0, o0, hh); softmax_lazy1(s1, m1, l1, o1, hh);
;             pv_sub2(kb + VOFF, VS, 64 * tt, s0, s1, o0, o1, r, hh);
;         }
;         __syncthreads();
;         bi = bn;
;     }
.LBB0_2822:
	s_add_i32 s4, s22, 1
	s_cmp_lg_u32 s22, 2
	s_cselect_b32 s50, s4, 0
	s_mul_i32 s4, s50, 0x5800
	s_add_i32 s6, s4, 0
	v_add3_u32 v0, s6, v179, v190
	s_waitcnt vmcnt(0)
	ds_write_b128 v0, v[152:155]
	s_and_saveexec_b64 s[4:5], s[0:1]
	v_add3_u32 v0, s6, v181, v185
	ds_write_b128 v0, v[148:151] offset:128
	s_or_b64 exec, exec, s[4:5]
	s_lshl_b32 s4, s47, 6
	s_add_i32 s96, s4, 0x80
	v_add_u32_e32 v0, s6, v195
	s_lshl_b64 s[6:7], s[96:97], 7
	v_lshl_add_u64 v[2:3], v[186:187], 0, s[6:7]
	global_load_dwordx4 v[152:155], v[2:3], off
	v_add_u32_e32 v0, s81, v0
	ds_write2_b64 v0, v[156:157], v[158:159] offset1:2
	s_and_saveexec_b64 s[6:7], s[0:1]
	s_cbranch_execz .LBB0_2826
	s_lshl_b64 s[24:25], s[96:97], 6
	v_lshl_add_u64 v[2:3], v[188:189], 0, s[24:25]
	flat_load_dwordx4 v[148:151], v[2:3]
.LBB0_2826:
	s_or_b64 exec, exec, s[6:7]
	s_mov_b32 s5, s97
	v_lshl_add_u64 v[2:3], s[4:5], 1, v[192:193]
	flat_load_dwordx4 v[156:159], v[2:3] offset:256
	s_mul_i32 s4, s22, 0x5800
	s_add_i32 s4, s4, 0
	v_add_u32_e32 v206, s4, v184
	v_add3_u32 v210, s4, v191, v197
	s_mov_b32 s48, 0
	s_mov_b64 s[22:23], -1
	s_branch .LBB0_2828
.LBB0_2827:
	v_add_f32_e32 v0, v211, v212
	v_add_f32_e32 v200, v200, v0
	v_cvt_pk_bf16_f32 v246, v84, v85
	v_cvt_pk_bf16_f32 v247, v86, v87
	v_cvt_pk_bf16_f32 v248, v88, v89
	v_cvt_pk_bf16_f32 v249, v90, v91
	v_cvt_pk_bf16_f32 v250, v92, v93
	v_cvt_pk_bf16_f32 v251, v94, v95
	v_cvt_pk_bf16_f32 v252, v96, v97
	v_cvt_pk_bf16_f32 v253, v98, v99
	v_lshl_add_u32 v0, s48, 6, v210
	ds_read_b128 v[84:87], v0 offset:13312
	ds_read_b128 v[88:91], v0 offset:17920
	ds_read_b128 v[92:95], v0 offset:13344
	ds_read_b128 v[96:99], v0 offset:17952
	s_xor_b64 s[4:5], s[22:23], -1
	v_exp_f32_e32 v0, v68
	v_exp_f32_e32 v3, v69
	v_exp_f32_e32 v211, v70
	v_exp_f32_e32 v212, v71
	v_add_f32_e32 v2, 0, v0
	v_exp_f32_e32 v213, v72
	v_add_f32_e32 v2, v3, v2
	v_exp_f32_e32 v214, v73
	v_add_f32_e32 v2, v211, v2
	v_exp_f32_e32 v215, v74
	v_add_f32_e32 v2, v212, v2
	s_waitcnt lgkmcnt(2)
	v_mfma_f32_32x32x16_bf16 v[4:19], v[84:87], v[246:249], v[4:19]
	v_exp_f32_e32 v216, v75
	v_add_f32_e32 v2, v213, v2
	v_exp_f32_e32 v76, v76
	v_add_f32_e32 v2, v214, v2
	v_exp_f32_e32 v77, v77
	v_mfma_f32_32x32x16_bf16 v[20:35], v[88:91], v[246:249], v[20:35]
	v_add_f32_e32 v2, v215, v2
	v_exp_f32_e32 v78, v78
	v_add_f32_e32 v2, v216, v2
	v_exp_f32_e32 v79, v79
	v_add_f32_e32 v2, v76, v2
	s_waitcnt lgkmcnt(0)
	v_mfma_f32_32x32x16_bf16 v[4:19], v[92:95], v[250:253], v[4:19]
	v_exp_f32_e32 v80, v80
	v_add_f32_e32 v2, v77, v2
	v_exp_f32_e32 v81, v81
	v_add_f32_e32 v2, v78, v2
	v_exp_f32_e32 v82, v82
	v_mfma_f32_32x32x16_bf16 v[20:35], v[96:99], v[250:253], v[20:35]
	v_add_f32_e32 v2, v79, v2
	v_exp_f32_e32 v83, v83
	v_add_f32_e32 v2, v80, v2
	v_add_f32_e32 v2, v81, v2
	v_add_f32_e32 v2, v82, v2
	v_add_f32_e32 v2, v83, v2
	v_mov_b32_e32 v68, v2
	v_cvt_pk_bf16_f32 v76, v76, v77
	v_cvt_pk_bf16_f32 v77, v78, v79
	v_cvt_pk_bf16_f32 v78, v80, v81
	v_cvt_pk_bf16_f32 v80, v0, v3
	v_permlane32_swap_b32_e32 v68, v2
	v_add_f32_e32 v2, v2, v68
	v_add_f32_e32 v196, v196, v2
	v_cvt_pk_bf16_f32 v79, v82, v83
	v_cvt_pk_bf16_f32 v81, v211, v212
	v_cvt_pk_bf16_f32 v82, v213, v214
	v_cvt_pk_bf16_f32 v83, v215, v216
	s_mov_b32 s48, 1
	s_mov_b64 s[22:23], 0
	s_and_b64 vcc, exec, s[4:5]
	v_mfma_f32_32x32x16_bf16 v[52:67], v[84:87], v[80:83], v[52:67]
	v_mfma_f32_32x32x16_bf16 v[36:51], v[88:91], v[80:83], v[36:51]
	v_mfma_f32_32x32x16_bf16 v[52:67], v[92:95], v[76:79], v[52:67]
	v_mfma_f32_32x32x16_bf16 v[36:51], v[96:99], v[76:79], v[36:51]
	s_cbranch_vccnz .LBB0_2844

; #define MLA_GLOAD(t) do { const size_t ko = (size_t)(64 * (t)); rk = *(const u32x4*)(gk + ko * 64); if (lo256) rr = *(const u32x4*)(gr + ko * 32); rv = *(const u32x4*)(gv + ko); } while (0)
; #define MLA_LSTORE(buf) do { LAS unsigned char* kb_ = lds + (buf) * TILE; *(LAS u32x4*)(kb_ + (tid >> 3) * KS + (tid & 7) * 16) = rk; \
;         if (lo256) *(LAS u32x4*)(kb_ + (tid >> 2) * KS + 128 + (tid & 3) * 16) = rr; lds_store16_as2x8(kb_ + VOFF + (tid >> 3) * VS + (tid & 7) * 16, rv); } while (0)
; DI void mla_qblock(int wv, int w, LAS unsigned char* lds, const bf16_t* Q, const bf16_t* KN, const bf16_t* KR, const bf16_t* VT, bf16_t* O, size_t tok0, int h, int qb) {
;     ...
;     for (int t = nfull; t < nt; ++t) {
;         const int bn = bi == 2 ? 0 : bi + 1;
;         if (t + 1 < nt) MLA_LSTORE(bn);
;         if (t + 2 < nt) MLA_GLOAD(t + 2);
.LBB0_2849:
	s_add_i32 s4, s50, 1
	s_cmp_lg_u32 s50, 2
	s_cselect_b32 s48, s4, 0
	s_add_i32 s49, s46, 1
	s_cmp_ge_u32 s49, s47
	s_cbranch_scc1 .LBB0_2854
	s_mul_i32 s4, s48, 0x5800
	s_add_i32 s6, s4, 0
	v_add3_u32 v0, s6, v179, v190
	s_waitcnt vmcnt(0)
	ds_write_b128 v0, v[152:155]
	s_and_saveexec_b64 s[4:5], s[0:1]
	v_add3_u32 v0, s6, v181, v185
	ds_write_b128 v0, v[148:151] offset:128
	s_or_b64 exec, exec, s[4:5]
	v_add_u32_e32 v0, s6, v195
	v_add_u32_e32 v0, s81, v0
	ds_write2_b64 v0, v[156:157], v[158:159] offset1:2
	s_add_i32 s4, s46, 2
	s_cmp_ge_u32 s4, s47
	s_cbranch_scc0 .LBB0_2855

; #define LAS __attribute__((address_space(3)))
; DI f32x16 mfma32(bf16x8 a, bf16x8 b, f32x16 c) { return __builtin_amdgcn_mfma_f32_32x32x16_bf16(a, b, c, 0, 0, 0); }
; DI int crow(int i, int hh) { return (i & 3) + 8 * (i >> 2) + 4 * hh; }
; #define MLA_GLOAD(t) do { const size_t ko = (size_t)(64 * (t)); rk = *(const u32x4*)(gk + ko * 64); if (lo256) rr = *(const u32x4*)(gr + ko * 32); rv = *(const u32x4*)(gv + ko); } while (0)
; DI void pv_sub2(const LAS unsigned char* vt, int vstride, int koff_bytes, const f32x16& p0, const f32x16& p1, f32x16 (&o0)[2], f32x16 (&o1)[2], int r, int hh) {
; #pragma unroll
;     for (int st = 0; st < 2; ++st) {
;         u32x2 lo[2], hi[2];
; #pragma unroll
;         for (int u = 0; u < 2; ++u) {
;             const LAS unsigned char* a = vt + (32 * u + r) * vstride + koff_bytes + 32 * st + 8 * hh;
;             lo[u] = *(const LAS u32x2*)a; hi[u] = *(const LAS u32x2*)(a + 16);
;         }
;         const bf16x8 pf0 = st ? pack8<1>(p0) : pack8<0>(p0), pf1 = st ? pack8<1>(p1) : pack8<0>(p1);
;         __builtin_amdgcn_sched_barrier(0);
; #pragma unroll
;         for (int u = 0; u < 2; ++u) { u32x4 v; v.x = lo[u].x; v.y = lo[u].y; v.z = hi[u].x; v.w = hi[u].y; const bf16x8 vf = __builtin_bit_cast(bf16x8, v);
;             o0[u] = mfma32(vf, pf0, o0[u]); o1[u] = mfma32(vf, pf1, o1[u]); }
;     }
; DI void mla_qblock(int wv, int w, LAS unsigned char* lds, const bf16_t* Q, const bf16_t* KN, const bf16_t* KR, const bf16_t* VT, bf16_t* O, size_t tok0, int h, int qb) {
;     ...
;     for (int t = nfull; t < nt; ++t) {
;         const int bn = bi == 2 ? 0 : bi + 1;
;         if (t + 1 < nt) MLA_LSTORE(bn);
;         if (t + 2 < nt) MLA_GLOAD(t + 2);
;         const int k0 = 64 * t;
;         if (k0 <= R0 + 63) {
;             const LAS unsigned char* kb = lds + bi * TILE;
; #pragma nounroll
;             for (int tt = 0; tt < 2; ++tt) {
;                 f32x16 s0, s1;
;                 MLA_QK1(tt);
; #pragma unroll
;                 for (int i = 0; i < 16; ++i) { const int key = k0 + 32 * tt + crow(i, hh); if (key > tq0) s0[i] = NEGF; if (key > tq1) s1[i] = NEGF; }
;                 softmax_lazy1(s0, m0, l0, o0, hh); softmax_lazy1(s1, m1, l1, o1, hh);
;                 pv_sub2(kb + VOFF, VS, 64 * tt, s0, s1, o0, o1, r, hh);
;             }
.LBB0_2858:
	s_mul_i32 s5, s50, 0x5800
	v_cmp_lt_i32_e32 vcc, v223, v222
	s_add_i32 s5, s5, 0
	v_add_u32_e32 v165, s5, v184
	v_cndmask_b32_e32 v0, v207, v223, vcc
	s_mov_b32 s46, 0
	v_lshlrev_b32_e32 v166, 2, v0
	v_add_u32_e32 v167, s5, v191
	v_or_b32_e32 v168, s4, v164
	s_mov_b64 s[22:23], -1
	s_branch .LBB0_2860
.LBB0_2859:
	v_add_f32_e32 v0, v169, v170
	v_add_f32_e32 v200, v200, v0
	v_cvt_pk_bf16_f32 v246, v68, v69
	v_cvt_pk_bf16_f32 v247, v70, v71
	v_cvt_pk_bf16_f32 v248, v72, v73
	v_cvt_pk_bf16_f32 v249, v74, v75
	v_cvt_pk_bf16_f32 v250, v76, v77
	v_cvt_pk_bf16_f32 v251, v78, v79
	v_cvt_pk_bf16_f32 v252, v80, v81
	v_cvt_pk_bf16_f32 v253, v82, v83
	v_lshl_add_u32 v2, s46, 6, v167
	v_add_u32_e32 v0, v2, v197
	v_add_u32_e32 v2, v2, v198
	v_add_u32_e32 v0, 0x3000, v0
	v_add_u32_e32 v2, 0x3000, v2
	ds_read_b128 v[68:71], v0 offset:1024
	ds_read_b128 v[72:75], v2 offset:1024
	ds_read_b128 v[76:79], v0 offset:1056
	ds_read_b128 v[80:83], v2 offset:1056
	s_xor_b64 s[4:5], s[22:23], -1
	v_exp_f32_e32 v0, v84
	v_exp_f32_e32 v3, v85
	v_exp_f32_e32 v84, v86
	v_exp_f32_e32 v85, v87
	v_add_f32_e32 v2, 0, v0
	v_exp_f32_e32 v86, v88
	v_add_f32_e32 v2, v3, v2
	v_exp_f32_e32 v87, v89
	v_add_f32_e32 v2, v84, v2
	v_exp_f32_e32 v88, v90
	v_add_f32_e32 v2, v85, v2
	s_waitcnt lgkmcnt(2)
	v_mfma_f32_32x32x16_bf16 v[4:19], v[68:71], v[246:249], v[4:19]
	v_exp_f32_e32 v89, v91
	v_add_f32_e32 v2, v86, v2
	v_exp_f32_e32 v90, v92
	v_add_f32_e32 v2, v87, v2
	v_exp_f32_e32 v91, v93
	v_mfma_f32_32x32x16_bf16 v[20:35], v[72:75], v[246:249], v[20:35]
	v_add_f32_e32 v2, v88, v2
	v_exp_f32_e32 v92, v94
	v_add_f32_e32 v2, v89, v2
	v_exp_f32_e32 v93, v95
	v_add_f32_e32 v2, v90, v2
	s_waitcnt lgkmcnt(0)
	v_mfma_f32_32x32x16_bf16 v[4:19], v[76:79], v[250:253], v[4:19]
	v_exp_f32_e32 v94, v96
	v_add_f32_e32 v2, v91, v2
	v_exp_f32_e32 v95, v97
	v_add_f32_e32 v2, v92, v2
	v_exp_f32_e32 v96, v98
	v_mfma_f32_32x32x16_bf16 v[20:35], v[80:83], v[250:253], v[20:35]
	v_add_f32_e32 v2, v93, v2
	v_exp_f32_e32 v97, v99
	v_add_f32_e32 v2, v94, v2
	v_add_f32_e32 v2, v95, v2
	v_add_f32_e32 v2, v96, v2
	v_add_f32_e32 v2, v97, v2
	v_mov_b32_e32 v98, v2
	s_nop 1
	v_permlane32_swap_b32_e32 v98, v2
	v_add_f32_e32 v2, v2, v98
	v_add_f32_e32 v196, v196, v2
	v_cvt_pk_bf16_f32 v246, v0, v3
	v_cvt_pk_bf16_f32 v247, v84, v85
	v_cvt_pk_bf16_f32 v248, v86, v87
	v_cvt_pk_bf16_f32 v249, v88, v89
	v_cvt_pk_bf16_f32 v250, v90, v91
	v_cvt_pk_bf16_f32 v251, v92, v93
	v_cvt_pk_bf16_f32 v252, v94, v95
	v_cvt_pk_bf16_f32 v253, v96, v97
	s_mov_b32 s46, 1
	s_mov_b64 s[22:23], 0
	s_andn2_b64 vcc, exec, s[4:5]
	v_mfma_f32_32x32x16_bf16 v[52:67], v[68:71], v[246:249], v[52:67]
	v_mfma_f32_32x32x16_bf16 v[36:51], v[72:75], v[246:249], v[36:51]
	v_mfma_f32_32x32x16_bf16 v[52:67], v[76:79], v[250:253], v[52:67]
	v_mfma_f32_32x32x16_bf16 v[36:51], v[80:83], v[250:253], v[36:51]
	s_cbranch_vccz .LBB0_2876
